# P0 transposes loop software-pipelined: next pair descriptors computed while loads in flight, next loads issued before barrier2/reads/stores of current pair
# speedup vs baseline: 1.0149x; 1.0006x over previous
.LBB0_54:
	s_and_b64 vcc, exec, s[0:1]
	s_cbranch_vccz .LBB0_133
	s_cmpk_gt_i32 s33, 0x143f
	s_cbranch_scc1 .LBB0_133
	s_lshl_b32 s50, s54, 1
	s_waitcnt lgkmcnt(0)
	s_add_u32 s51, s42, 0xc800000
	s_addc_u32 s52, s43, 0
	s_add_u32 s53, s42, 0xc400000
	s_addc_u32 s55, s43, 0
	s_add_u32 s56, s42, 0xc000000
	s_addc_u32 s57, s43, 0
	s_add_u32 s58, s42, 0xbc00000
	s_addc_u32 s59, s43, 0
	s_add_u32 s60, s42, 0xac00000
	s_addc_u32 s61, s43, 0
	s_add_u32 s62, s42, 0xa000000
	s_addc_u32 s63, s43, 0
	s_lshl_b32 s64, s33, 6
	s_lshl_b32 s65, s54, 7
	s_lshl_b32 s66, s33, 1
	s_lshl_b32 s67, s54, 2
	s_lshl_b32 s68, s33, 2
	s_lshl_b32 s69, s54, 3
	s_mov_b32 s7, 0
	v_mov_b32_e32 v35, 0
	v_mov_b32_e32 v135, 0
	s_mov_b32 s89, 0
	s_mov_b32 s79, 0
	s_mov_b32 s83, 0
	s_branch .LBB0_58
.Ltr_top:
	s_mov_b32 s89, 1
	s_mov_b32 s72, s17
	s_mov_b32 s73, s70
	s_mov_b64 s[74:75], s[2:3]
	s_mov_b64 s[76:77], s[8:9]
	s_mov_b32 s78, s6
	s_mov_b64 s[80:81], s[12:13]
	s_mov_b32 s82, s16
	s_mov_b64 s[84:85], s[42:43]
	s_mov_b64 s[86:87], s[22:23]
	s_add_i32 s33, s33, s50
	s_add_i32 s64, s64, s65
	s_add_i32 s66, s66, s67
	s_add_i32 s68, s68, s69
	s_cmpk_lt_i32 s33, 0x1440
	s_cselect_b32 s88, 1, 0
	s_cbranch_scc0 .Ltr_w

.LBB0_112:
	s_cmp_eq_u32 s89, 0
	s_cbranch_scc1 .Ltr_loads
.Ltr_w:
	s_barrier
	s_waitcnt vmcnt(0)
	ds_write2_b32 v34, v6, v7 offset1:1
	ds_write2_b32 v34, v8, v9 offset0:2 offset1:3
	v_add_u32_e32 v6, 0x4140, v34
	ds_write2_b32 v6, v2, v3 offset1:1
	v_add_u32_e32 v2, 0x4148, v34
	ds_write2_b32 v2, v4, v5 offset1:1
	v_add_u32_e32 v2, 0x1040, v34
	ds_write2_b32 v2, v14, v15 offset1:1
	v_add_u32_e32 v2, 0x1048, v34
	ds_write2_b32 v2, v16, v17 offset1:1
	v_add_u32_e32 v2, 0x5180, v34
	ds_write2_b32 v2, v10, v11 offset1:1
	v_add_u32_e32 v2, 0x5188, v34
	ds_write2_b32 v2, v12, v13 offset1:1
	v_add_u32_e32 v2, 0x2080, v34
	ds_write2_b32 v2, v22, v23 offset1:1
	v_add_u32_e32 v2, 0x2088, v34
	ds_write2_b32 v2, v24, v25 offset1:1
	v_add_u32_e32 v2, 0x61c0, v34
	ds_write2_b32 v2, v18, v19 offset1:1
	v_add_u32_e32 v2, 0x61c8, v34
	ds_write2_b32 v2, v20, v21 offset1:1
	v_add_u32_e32 v2, 0x30c0, v34
	ds_write2_b32 v2, v30, v31 offset1:1
	v_add_u32_e32 v2, 0x30c8, v34
	ds_write2_b32 v2, v32, v33 offset1:1
	v_add_u32_e32 v2, 0x7200, v34
	ds_write2_b32 v2, v26, v27 offset1:1
	v_add_u32_e32 v2, 0x7208, v34
	ds_write2_b32 v2, v28, v29 offset1:1
	s_cmp_eq_u32 s88, 0
	s_cbranch_scc1 .Ltr_b2

.LBB0_128:
	s_or_b64 exec, exec, s[10:11]
	v_lshl_add_u32 v34, v38, 6, v38
	v_add_lshl_u32 v34, v34, v39, 2
	s_cmp_eq_u32 s89, 0
	s_cbranch_scc1 .Ltr_top
.Ltr_b2:
	s_waitcnt lgkmcnt(0)
	s_barrier
	v_mov_b32_e32 v101, v206
	v_lshlrev_b32_e32 v103, 4, v101
	v_and_b32_e32 v103, 48, v103
	v_ashrrev_i32_e32 v102, 2, v101
	v_and_b32_e32 v101, -4, v101
	v_mul_u32_u24_e32 v104, 0x41, v103
	v_lshl_add_u32 v101, v104, 2, v101
	v_add_u32_e32 v106, 0x400, v101
	v_add_u32_e32 v120, s72, v102
	ds_read2_b32 v[108:109], v101 offset1:65
	ds_read2_b32 v[104:105], v101 offset0:130 offset1:195
	ds_read2_b32 v[110:111], v106 offset0:4 offset1:69
	ds_read2_b32 v[106:107], v106 offset0:134 offset1:199
	v_add_u32_e32 v114, 0x800, v101
	v_add_u32_e32 v118, 0xc00, v101
	v_ashrrev_i32_e32 v121, 31, v120
	ds_read2_b32 v[112:113], v114 offset0:8 offset1:73
	ds_read2_b32 v[114:115], v114 offset0:138 offset1:203
	ds_read2_b32 v[116:117], v118 offset0:12 offset1:77
	ds_read2_b32 v[118:119], v118 offset0:142 offset1:207
	v_mul_lo_u32 v122, s74, v121
	v_mul_lo_u32 v123, s75, v120
	v_mad_u64_u32 v[120:121], s[90:91], s74, v120, 0
	v_add3_u32 v121, v121, v122, v123
	v_lshl_add_u64 v[120:121], v[120:121], 1, s[76:77]
	v_lshl_add_u64 v[120:121], s[78:79], 1, v[120:121]
	v_lshlrev_b32_e32 v134, 1, v103
	v_lshl_add_u64 v[120:121], v[120:121], 0, v[134:135]
	s_waitcnt lgkmcnt(4)
	v_cvt_pk_bf16_f32 v107, v106, v107
	v_cvt_pk_bf16_f32 v106, v110, v111
	v_cvt_pk_bf16_f32 v105, v104, v105
	v_cvt_pk_bf16_f32 v104, v108, v109
	global_store_dwordx4 v[120:121], v[104:107], off
	s_andn2_b64 vcc, exec, s[80:81]
	s_waitcnt lgkmcnt(0)
	v_cvt_pk_bf16_f32 v107, v118, v119
	v_cvt_pk_bf16_f32 v106, v116, v117
	v_cvt_pk_bf16_f32 v105, v114, v115
	v_cvt_pk_bf16_f32 v104, v112, v113
	global_store_dwordx4 v[120:121], v[104:107], off offset:16
	s_cbranch_vccnz .Ltr_post
	v_add_u32_e32 v103, 0x4000, v101
	ds_read2_b32 v[106:107], v103 offset0:80 offset1:145
	v_add_u32_e32 v103, 0x4200, v101
	ds_read2_b32 v[108:109], v103 offset0:82 offset1:147
	v_add_u32_e32 v103, 0x4400, v101
	ds_read2_b32 v[110:111], v103 offset0:84 offset1:149
	v_add_u32_e32 v103, 0x4600, v101
	ds_read2_b32 v[104:105], v103 offset0:86 offset1:151
	v_add_u32_e32 v103, 0x4800, v101
	ds_read2_b32 v[112:113], v103 offset0:88 offset1:153
	v_add_u32_e32 v103, 0x4a00, v101
	ds_read2_b32 v[114:115], v103 offset0:90 offset1:155
	v_add_u32_e32 v103, 0x4c00, v101
	v_add_u32_e32 v101, 0x4e00, v101
	ds_read2_b32 v[118:119], v101 offset0:94 offset1:159
	v_add_u32_e32 v101, s73, v102
	v_ashrrev_i32_e32 v102, 31, v101
	ds_read2_b32 v[116:117], v103 offset0:92 offset1:157
	v_mul_lo_u32 v120, s84, v102
	v_mul_lo_u32 v121, s85, v101
	v_mad_u64_u32 v[102:103], s[90:91], s84, v101, 0
	v_add3_u32 v103, v103, v120, v121
	v_lshl_add_u64 v[102:103], v[102:103], 1, s[86:87]
	v_lshl_add_u64 v[102:103], s[82:83], 1, v[102:103]
	v_lshl_add_u64 v[120:121], v[102:103], 0, v[134:135]
	s_waitcnt lgkmcnt(4)
	v_cvt_pk_bf16_f32 v105, v104, v105
	v_cvt_pk_bf16_f32 v104, v110, v111
	v_cvt_pk_bf16_f32 v103, v108, v109
	v_cvt_pk_bf16_f32 v102, v106, v107
	global_store_dwordx4 v[120:121], v[102:105], off
	s_waitcnt lgkmcnt(1)
	s_nop 0
	v_cvt_pk_bf16_f32 v105, v118, v119
	s_waitcnt lgkmcnt(0)
	v_cvt_pk_bf16_f32 v104, v116, v117
	v_cvt_pk_bf16_f32 v103, v114, v115
	v_cvt_pk_bf16_f32 v102, v112, v113
	global_store_dwordx4 v[120:121], v[102:105], off offset:16
	s_branch .Ltr_post
.Ltr_post:
	s_cmp_eq_u32 s88, 0
	s_cbranch_scc0 .Ltr_top
	s_branch .LBB0_133
